# UQ GEMM: early epilogue alignment barrier too (vcc scratch), on top of v48
# speedup vs baseline: 1.0043x; 1.0019x over previous
; #define wt16(p, v) wt16b(WSB, (p), (v))
; __device__ __forceinline__ u32x4 pack8(const float (&f)[8]) { u32x4 v; v.x = cvt_pk_bf16(f[0], f[1]); v.y = cvt_pk_bf16(f[2], f[3]); v.z = cvt_pk_bf16(f[4], f[5]); v.w = cvt_pk_bf16(f[6], f[7]); return v; }
; __device__ __forceinline__ float sum4q(const f32x4 a) { return (a[0] + a[1]) + (a[2] + a[3]); }
;     __device__ __forceinline__ void operator()(const f32x4 (&acc)[2][2][4][2], const pg8::Unit& u, int wr, int wc, int fr, int fq) const {
;         const int row0 = u.pm * 256 + wr * 64 + fr, col0 = u.pn * 256 + wc * 32 + 8 * fq;
;         f32x4 rq[2][4];
; #pragma unroll
;         for (int ai = 0; ai < 2; ++ai)
; #pragma unroll
;             for (int m = 0; m < 4; ++m) rq[ai][m] = *(const f32x4*)(qss + (size_t)(row0 + ai * 128 + m * 16) * 4);
; #pragma unroll
;         for (int ai = 0; ai < 2; ++ai)
; #pragma unroll
;             for (int m = 0; m < 4; ++m) {
;                 const int row = row0 + ai * 128 + m * 16; const float r = rsqrtf(sum4q(rq[ai][m]) * (1.f / 256.f) + EPS);
; #pragma unroll
;                 for (int bj = 0; bj < 2; ++bj) {
;                     float v[8];
; #pragma unroll
;                     for (int n = 0; n < 2; ++n)
; #pragma unroll
;                         for (int i = 0; i < 4; ++i) v[4 * n + i] = acc[ai][bj][m][n][i] * r;
;                     wt16(O + (size_t)row * 768 + col0 + bj * 128, pack8(v));
;                 }
;             }
.LBB0_104:
	s_and_b64 vcc, exec, s[40:41]
	s_cbranch_scc0 .Lea_s1
	s_cmpk_gt_u32 s13, 0xff
	s_cbranch_scc1 .Lea_s1
	s_barrier
	s_mov_b32 vcc_lo, 1
	s_nop 0
	v_writelane_b32 v255, vcc_lo, 43
.Lea_s1:
	s_nop 0
	v_lshl_add_u32 v184, s59, 8, v171
	v_readlane_b32 s2, v253, 24
	v_ashrrev_i32_e32 v185, 31, v184
	v_readlane_b32 s3, v253, 25
	v_or_b32_e32 v174, 16, v184
	v_ashrrev_i32_e32 v175, 31, v174
	v_lshl_add_u64 v[130:131], v[184:185], 4, s[2:3]
	global_load_dwordx4 v[164:167], v[130:131], off
	v_lshl_add_u64 v[132:133], v[174:175], 4, s[2:3]
	global_load_dwordx4 v[180:183], v[132:133], off
	v_or_b32_e32 v172, 32, v184
	v_ashrrev_i32_e32 v173, 31, v172
	v_lshl_add_u64 v[132:133], v[172:173], 4, s[2:3]
	global_load_dwordx4 v[150:153], v[132:133], off
	v_or_b32_e32 v168, 48, v184
	v_ashrrev_i32_e32 v169, 31, v168
	v_lshl_add_u64 v[132:133], v[168:169], 4, s[2:3]
	global_load_dwordx4 v[146:149], v[132:133], off
	global_load_dwordx4 v[142:145], v[130:131], off offset:2048
	global_load_dwordx4 v[138:141], v[130:131], off offset:2304
	global_load_dwordx4 v[134:137], v[130:131], off offset:2560
	s_nop 0
	global_load_dwordx4 v[130:133], v[130:131], off offset:2816
	v_lshl_or_b32 v170, s58, 9, v178
	s_movk_i32 s23, 0x600
	s_mov_b32 s26, 0x3b800000
	s_mov_b32 s58, s62
	s_mov_b32 s59, s63
	s_mov_b64 s[46:47], s[24:25]
	s_waitcnt vmcnt(0)
	v_mov_b32_e32 v186, v165
	v_mov_b32_e32 v187, v166
	v_mov_b32_e32 v165, v167
	v_pk_add_f32 v[166:167], v[186:187], v[164:165]
	v_mad_u64_u32 v[164:165], s[2:3], v184, s23, v[170:171]
	v_mov_b32_e32 v184, v181
	v_mov_b32_e32 v185, v182
	v_mov_b32_e32 v181, v183
	v_pk_add_f32 v[180:181], v[184:185], v[180:181]
	v_mov_b32_e32 v183, v166
	v_mov_b32_e32 v182, v180
	v_mov_b32_e32 v166, v181
	s_mov_b32 s2, 0x358637bd
	v_pk_add_f32 v[180:181], v[182:183], v[166:167]
	v_mov_b64_e32 v[166:167], s[2:3]
	v_pk_fma_f32 v[180:181], v[180:181], s[26:27], v[166:167] op_sel_hi:[1,0,0]
	v_add_u32_e32 v165, 0x14a00000, v164
	v_mul_f32_e32 v169, 0x4b800000, v181
	v_cmp_gt_f32_e64 s[42:43], s83, v181
	v_cmp_gt_f32_e32 vcc, s83, v180
	s_mov_b32 s2, 0x14a00000
	v_cndmask_b32_e64 v169, v181, v169, s[42:43]
	v_rsq_f32_e32 v169, v169
	s_nop 0
	v_mul_f32_e32 v173, 0x45800000, v169
	v_cndmask_b32_e64 v182, v169, v173, s[42:43]
	v_pk_mul_f32 v[122:123], v[122:123], v[182:183] op_sel_hi:[1,0]
	v_pk_mul_f32 v[124:125], v[124:125], v[182:183] op_sel_hi:[1,0]
	v_pk_mul_f32 v[126:127], v[126:127], v[182:183] op_sel_hi:[1,0]
	v_pk_mul_f32 v[128:129], v[128:129], v[182:183] op_sel_hi:[1,0]
	v_cvt_pk_bf16_f32 v122, v122, v123
	v_cvt_pk_bf16_f32 v123, v124, v125
	v_cvt_pk_bf16_f32 v124, v126, v127
	v_cvt_pk_bf16_f32 v125, v128, v129
	buffer_store_dwordx4 v[122:125], v165, s[56:59], 0 offen sc1
	v_pk_mul_f32 v[118:119], v[118:119], v[182:183] op_sel_hi:[1,0]
	v_pk_mul_f32 v[120:121], v[120:121], v[182:183] op_sel_hi:[1,0]
	v_pk_mul_f32 v[122:123], v[114:115], v[182:183] op_sel_hi:[1,0]
	v_pk_mul_f32 v[124:125], v[116:117], v[182:183] op_sel_hi:[1,0]
	v_cvt_pk_bf16_f32 v114, v118, v119
	v_cvt_pk_bf16_f32 v115, v120, v121
	v_cvt_pk_bf16_f32 v116, v122, v123
	v_cvt_pk_bf16_f32 v117, v124, v125
	buffer_store_dwordx4 v[114:117], v165, s[56:59], 0 offen offset:256 sc1
	s_nop 1
	v_mul_f32_e32 v114, 0x4b800000, v180
	v_cndmask_b32_e32 v114, v180, v114, vcc
	v_rsq_f32_e32 v114, v114
	s_nop 0
	v_mul_f32_e32 v115, 0x45800000, v114
	v_cndmask_b32_e32 v114, v114, v115, vcc
	v_mul_lo_u32 v115, v174, s23
	v_pk_mul_f32 v[110:111], v[110:111], v[114:115] op_sel_hi:[1,0]
	v_pk_mul_f32 v[112:113], v[112:113], v[114:115] op_sel_hi:[1,0]
	v_pk_mul_f32 v[116:117], v[106:107], v[114:115] op_sel_hi:[1,0]
	v_pk_mul_f32 v[118:119], v[108:109], v[114:115] op_sel_hi:[1,0]
	v_cvt_pk_bf16_f32 v106, v110, v111
	v_cvt_pk_bf16_f32 v107, v112, v113
	v_cvt_pk_bf16_f32 v108, v116, v117
	v_cvt_pk_bf16_f32 v109, v118, v119
	v_add3_u32 v110, v115, v170, s2
	buffer_store_dwordx4 v[106:109], v110, s[56:59], 0 offen sc1
	v_pk_mul_f32 v[102:103], v[102:103], v[114:115] op_sel_hi:[1,0]
	v_pk_mul_f32 v[104:105], v[104:105], v[114:115] op_sel_hi:[1,0]
	v_pk_mul_f32 v[106:107], v[98:99], v[114:115] op_sel_hi:[1,0]
	v_pk_mul_f32 v[108:109], v[100:101], v[114:115] op_sel_hi:[1,0]
	v_cvt_pk_bf16_f32 v98, v102, v103
	v_cvt_pk_bf16_f32 v99, v104, v105
	v_cvt_pk_bf16_f32 v100, v106, v107
	v_cvt_pk_bf16_f32 v101, v108, v109
	buffer_store_dwordx4 v[98:101], v110, s[56:59], 0 offen offset:256 sc1
	s_nop 1
	v_mul_lo_u32 v100, v172, s23
	v_mov_b32_e32 v98, v151
	v_mov_b32_e32 v99, v152
	v_mov_b32_e32 v151, v153
	v_add3_u32 v106, v100, v170, s2
	v_mov_b32_e32 v100, v147
	v_mov_b32_e32 v101, v148
	v_mov_b32_e32 v147, v149
	v_pk_add_f32 v[98:99], v[98:99], v[150:151]
	v_pk_add_f32 v[100:101], v[100:101], v[146:147]
	v_mov_b32_e32 v103, v98
	v_mov_b32_e32 v102, v100
	v_mov_b32_e32 v98, v101
	v_pk_add_f32 v[98:99], v[102:103], v[98:99]
	s_nop 0
	v_pk_fma_f32 v[98:99], v[98:99], s[26:27], v[166:167] op_sel_hi:[1,0,0]
	s_nop 0
	v_mul_f32_e32 v100, 0x4b800000, v99
	v_cmp_gt_f32_e64 s[42:43], s83, v99
	v_cmp_gt_f32_e32 vcc, s83, v98
	s_nop 0
	v_cndmask_b32_e64 v99, v99, v100, s[42:43]
	v_rsq_f32_e32 v99, v99
	s_nop 0
	v_mul_f32_e32 v100, 0x45800000, v99
	v_cndmask_b32_e64 v100, v99, v100, s[42:43]
	v_pk_mul_f32 v[94:95], v[94:95], v[100:101] op_sel_hi:[1,0]
	v_pk_mul_f32 v[96:97], v[96:97], v[100:101] op_sel_hi:[1,0]
	v_pk_mul_f32 v[102:103], v[90:91], v[100:101] op_sel_hi:[1,0]
	v_pk_mul_f32 v[104:105], v[92:93], v[100:101] op_sel_hi:[1,0]
	v_cvt_pk_bf16_f32 v90, v94, v95
	v_cvt_pk_bf16_f32 v91, v96, v97
	v_cvt_pk_bf16_f32 v92, v102, v103
	v_cvt_pk_bf16_f32 v93, v104, v105
	buffer_store_dwordx4 v[90:93], v106, s[56:59], 0 offen sc1
; #define wt16(p, v) wt16b(WSB, (p), (v))
; __device__ __forceinline__ u32x4 pack8(const float (&f)[8]) { u32x4 v; v.x = cvt_pk_bf16(f[0], f[1]); v.y = cvt_pk_bf16(f[2], f[3]); v.z = cvt_pk_bf16(f[4], f[5]); v.w = cvt_pk_bf16(f[6], f[7]); return v; }
; __device__ __forceinline__ float sum4q(const f32x4 a) { return (a[0] + a[1]) + (a[2] + a[3]); }
;     __device__ __forceinline__ void operator()(const f32x4 (&acc)[2][2][4][2], const pg8::Unit& u, int wr, int wc, int fr, int fq) const {
;     ...
;         for (int ai = 0; ai < 2; ++ai)
; #pragma unroll
;             for (int m = 0; m < 4; ++m) {
;                 const int row = row0 + ai * 128 + m * 16; const float r = rsqrtf(sum4q(rq[ai][m]) * (1.f / 256.f) + EPS);
; #pragma unroll
;                 for (int bj = 0; bj < 2; ++bj) {
;                     float v[8];
; #pragma unroll
;                     for (int n = 0; n < 2; ++n)
; #pragma unroll
;                         for (int i = 0; i < 4; ++i) v[4 * n + i] = acc[ai][bj][m][n][i] * r;
;                     wt16(O + (size_t)row * 768 + col0 + bj * 128, pack8(v));
;                 }
;             }
	v_pk_mul_f32 v[86:87], v[86:87], v[100:101] op_sel_hi:[1,0]
	v_pk_mul_f32 v[88:89], v[88:89], v[100:101] op_sel_hi:[1,0]
	v_pk_mul_f32 v[90:91], v[82:83], v[100:101] op_sel_hi:[1,0]
	v_pk_mul_f32 v[92:93], v[84:85], v[100:101] op_sel_hi:[1,0]
	v_cvt_pk_bf16_f32 v82, v86, v87
	v_cvt_pk_bf16_f32 v83, v88, v89
	v_cvt_pk_bf16_f32 v84, v90, v91
	v_cvt_pk_bf16_f32 v85, v92, v93
	buffer_store_dwordx4 v[82:85], v106, s[56:59], 0 offen offset:256 sc1
	s_nop 1
	v_mul_f32_e32 v82, 0x4b800000, v98
	v_cndmask_b32_e32 v82, v98, v82, vcc
	v_rsq_f32_e32 v82, v82
	s_nop 0
	v_mul_f32_e32 v83, 0x45800000, v82
	v_cndmask_b32_e32 v82, v82, v83, vcc
	v_mul_lo_u32 v83, v168, s23
	v_pk_mul_f32 v[78:79], v[78:79], v[82:83] op_sel_hi:[1,0]
	v_pk_mul_f32 v[80:81], v[80:81], v[82:83] op_sel_hi:[1,0]
	v_pk_mul_f32 v[84:85], v[74:75], v[82:83] op_sel_hi:[1,0]
	v_pk_mul_f32 v[86:87], v[76:77], v[82:83] op_sel_hi:[1,0]
	v_cvt_pk_bf16_f32 v74, v78, v79
	v_cvt_pk_bf16_f32 v75, v80, v81
	v_cvt_pk_bf16_f32 v76, v84, v85
	v_cvt_pk_bf16_f32 v77, v86, v87
	v_add3_u32 v78, v83, v170, s2
	buffer_store_dwordx4 v[74:77], v78, s[56:59], 0 offen sc1
	v_pk_mul_f32 v[70:71], v[70:71], v[82:83] op_sel_hi:[1,0]
	v_pk_mul_f32 v[72:73], v[72:73], v[82:83] op_sel_hi:[1,0]
	v_pk_mul_f32 v[74:75], v[66:67], v[82:83] op_sel_hi:[1,0]
	v_pk_mul_f32 v[76:77], v[68:69], v[82:83] op_sel_hi:[1,0]
	v_cvt_pk_bf16_f32 v66, v70, v71
	v_cvt_pk_bf16_f32 v67, v72, v73
	v_cvt_pk_bf16_f32 v68, v74, v75
	v_cvt_pk_bf16_f32 v69, v76, v77
	buffer_store_dwordx4 v[66:69], v78, s[56:59], 0 offen offset:256 sc1
	v_add_u32_e32 v74, 0x14a30000, v164
	s_nop 0
	v_mov_b32_e32 v66, v143
	v_mov_b32_e32 v67, v144
	v_mov_b32_e32 v143, v145
	v_mov_b32_e32 v68, v139
	v_mov_b32_e32 v69, v140
	v_mov_b32_e32 v139, v141
	v_pk_add_f32 v[66:67], v[66:67], v[142:143]
	v_pk_add_f32 v[68:69], v[68:69], v[138:139]
	v_mov_b32_e32 v71, v66
	v_mov_b32_e32 v70, v68
	v_mov_b32_e32 v66, v69
	v_pk_add_f32 v[66:67], v[70:71], v[66:67]
	s_nop 0
	v_pk_fma_f32 v[66:67], v[66:67], s[26:27], v[166:167] op_sel_hi:[1,0,0]
	s_nop 0
	v_mul_f32_e32 v68, 0x4b800000, v67
	v_cmp_gt_f32_e64 s[42:43], s83, v67
	v_cmp_gt_f32_e32 vcc, s83, v66
	s_nop 0
	v_cndmask_b32_e64 v67, v67, v68, s[42:43]
	v_rsq_f32_e32 v67, v67
	s_nop 0
	v_mul_f32_e32 v68, 0x45800000, v67
	v_cndmask_b32_e64 v68, v67, v68, s[42:43]
	v_pk_mul_f32 v[62:63], v[62:63], v[68:69] op_sel_hi:[1,0]
	v_pk_mul_f32 v[64:65], v[64:65], v[68:69] op_sel_hi:[1,0]
	v_pk_mul_f32 v[70:71], v[58:59], v[68:69] op_sel_hi:[1,0]
	v_pk_mul_f32 v[72:73], v[60:61], v[68:69] op_sel_hi:[1,0]
	v_cvt_pk_bf16_f32 v58, v62, v63
	v_cvt_pk_bf16_f32 v59, v64, v65
	v_cvt_pk_bf16_f32 v60, v70, v71
	v_cvt_pk_bf16_f32 v61, v72, v73
	buffer_store_dwordx4 v[58:61], v74, s[56:59], 0 offen sc1
	v_pk_mul_f32 v[54:55], v[54:55], v[68:69] op_sel_hi:[1,0]
	v_pk_mul_f32 v[56:57], v[56:57], v[68:69] op_sel_hi:[1,0]
	v_pk_mul_f32 v[58:59], v[50:51], v[68:69] op_sel_hi:[1,0]
	v_pk_mul_f32 v[60:61], v[52:53], v[68:69] op_sel_hi:[1,0]
	v_cvt_pk_bf16_f32 v50, v54, v55
	v_cvt_pk_bf16_f32 v51, v56, v57
	v_cvt_pk_bf16_f32 v52, v58, v59
	v_cvt_pk_bf16_f32 v53, v60, v61
	buffer_store_dwordx4 v[50:53], v74, s[56:59], 0 offen offset:256 sc1
	s_nop 1
	v_mul_f32_e32 v50, 0x4b800000, v66
	v_cndmask_b32_e32 v50, v66, v50, vcc
	v_rsq_f32_e32 v50, v50
	s_nop 0
	v_mul_f32_e32 v51, 0x45800000, v50
	v_cndmask_b32_e32 v50, v50, v51, vcc
	v_pk_mul_f32 v[46:47], v[46:47], v[50:51] op_sel_hi:[1,0]
	v_pk_mul_f32 v[48:49], v[48:49], v[50:51] op_sel_hi:[1,0]
	v_pk_mul_f32 v[52:53], v[42:43], v[50:51] op_sel_hi:[1,0]
; #define wt16(p, v) wt16b(WSB, (p), (v))
; __device__ __forceinline__ u32x4 pack8(const float (&f)[8]) { u32x4 v; v.x = cvt_pk_bf16(f[0], f[1]); v.y = cvt_pk_bf16(f[2], f[3]); v.z = cvt_pk_bf16(f[4], f[5]); v.w = cvt_pk_bf16(f[6], f[7]); return v; }
; __device__ __forceinline__ float sum4q(const f32x4 a) { return (a[0] + a[1]) + (a[2] + a[3]); }
; template <class Epi, class Sched, bool ALIGN_EPI>
; __device__ __forceinline__ void gemm_phase(PG8_LAS unsigned char* lds, const Gemm g, const Sched& S, const Epi& E) {
;     ...
;         if (!has_next) break;
;     __device__ __forceinline__ void operator()(const f32x4 (&acc)[2][2][4][2], const pg8::Unit& u, int wr, int wc, int fr, int fq) const {
;     ...
;         for (int ai = 0; ai < 2; ++ai)
; #pragma unroll
;             for (int m = 0; m < 4; ++m) {
;                 const int row = row0 + ai * 128 + m * 16; const float r = rsqrtf(sum4q(rq[ai][m]) * (1.f / 256.f) + EPS);
; #pragma unroll
;                 for (int bj = 0; bj < 2; ++bj) {
;                     float v[8];
; #pragma unroll
;                     for (int n = 0; n < 2; ++n)
; #pragma unroll
;                         for (int i = 0; i < 4; ++i) v[4 * n + i] = acc[ai][bj][m][n][i] * r;
;                     wt16(O + (size_t)row * 768 + col0 + bj * 128, pack8(v));
;                 }
;             }
	v_pk_mul_f32 v[54:55], v[44:45], v[50:51] op_sel_hi:[1,0]
	v_cvt_pk_bf16_f32 v42, v46, v47
	v_cvt_pk_bf16_f32 v43, v48, v49
	v_cvt_pk_bf16_f32 v44, v52, v53
	v_cvt_pk_bf16_f32 v45, v54, v55
	v_add_u32_e32 v46, 0x14a36000, v164
	buffer_store_dwordx4 v[42:45], v46, s[56:59], 0 offen sc1
	v_pk_mul_f32 v[38:39], v[38:39], v[50:51] op_sel_hi:[1,0]
	v_pk_mul_f32 v[40:41], v[40:41], v[50:51] op_sel_hi:[1,0]
	v_pk_mul_f32 v[42:43], v[34:35], v[50:51] op_sel_hi:[1,0]
	v_pk_mul_f32 v[44:45], v[36:37], v[50:51] op_sel_hi:[1,0]
	v_cvt_pk_bf16_f32 v34, v38, v39
	v_cvt_pk_bf16_f32 v35, v40, v41
	v_cvt_pk_bf16_f32 v36, v42, v43
	v_cvt_pk_bf16_f32 v37, v44, v45
	buffer_store_dwordx4 v[34:37], v46, s[56:59], 0 offen offset:256 sc1
	v_add_u32_e32 v42, 0x14a3c000, v164
	s_nop 0
	v_mov_b32_e32 v34, v135
	v_mov_b32_e32 v35, v136
	v_mov_b32_e32 v135, v137
	v_mov_b32_e32 v36, v131
	v_mov_b32_e32 v37, v132
	v_mov_b32_e32 v131, v133
	v_pk_add_f32 v[34:35], v[34:35], v[134:135]
	v_pk_add_f32 v[36:37], v[36:37], v[130:131]
	v_mov_b32_e32 v39, v34
	v_mov_b32_e32 v38, v36
	v_mov_b32_e32 v34, v37
	v_pk_add_f32 v[34:35], v[38:39], v[34:35]
	s_nop 0
	v_pk_fma_f32 v[34:35], v[34:35], s[26:27], v[166:167] op_sel_hi:[1,0,0]
	s_mov_b64 s[26:27], s[44:45]
	v_mul_f32_e32 v36, 0x4b800000, v35
	v_cmp_gt_f32_e64 s[42:43], s83, v35
	v_cmp_gt_f32_e32 vcc, s83, v34
	s_nop 0
	v_cndmask_b32_e64 v35, v35, v36, s[42:43]
	v_rsq_f32_e32 v35, v35
	s_nop 0
	v_mul_f32_e32 v36, 0x45800000, v35
	v_cndmask_b32_e64 v36, v35, v36, s[42:43]
	v_pk_mul_f32 v[30:31], v[30:31], v[36:37] op_sel_hi:[1,0]
	v_pk_mul_f32 v[32:33], v[32:33], v[36:37] op_sel_hi:[1,0]
	v_pk_mul_f32 v[38:39], v[26:27], v[36:37] op_sel_hi:[1,0]
	v_pk_mul_f32 v[40:41], v[28:29], v[36:37] op_sel_hi:[1,0]
	v_cvt_pk_bf16_f32 v26, v30, v31
	v_cvt_pk_bf16_f32 v27, v32, v33
	v_cvt_pk_bf16_f32 v28, v38, v39
	v_cvt_pk_bf16_f32 v29, v40, v41
	buffer_store_dwordx4 v[26:29], v42, s[56:59], 0 offen sc1
	v_pk_mul_f32 v[22:23], v[22:23], v[36:37] op_sel_hi:[1,0]
	v_pk_mul_f32 v[24:25], v[24:25], v[36:37] op_sel_hi:[1,0]
	v_pk_mul_f32 v[26:27], v[18:19], v[36:37] op_sel_hi:[1,0]
	v_pk_mul_f32 v[28:29], v[20:21], v[36:37] op_sel_hi:[1,0]
	v_cvt_pk_bf16_f32 v18, v22, v23
	v_cvt_pk_bf16_f32 v19, v24, v25
	v_cvt_pk_bf16_f32 v20, v26, v27
	v_cvt_pk_bf16_f32 v21, v28, v29
	buffer_store_dwordx4 v[18:21], v42, s[56:59], 0 offen offset:256 sc1
	s_nop 1
	v_mul_f32_e32 v18, 0x4b800000, v34
	v_cndmask_b32_e32 v18, v34, v18, vcc
	v_rsq_f32_e32 v18, v18
	s_nop 0
	v_mul_f32_e32 v19, 0x45800000, v18
	v_cndmask_b32_e32 v18, v18, v19, vcc
	v_pk_mul_f32 v[14:15], v[14:15], v[18:19] op_sel_hi:[1,0]
	v_pk_mul_f32 v[16:17], v[16:17], v[18:19] op_sel_hi:[1,0]
	v_pk_mul_f32 v[20:21], v[10:11], v[18:19] op_sel_hi:[1,0]
	v_pk_mul_f32 v[22:23], v[12:13], v[18:19] op_sel_hi:[1,0]
	v_cvt_pk_bf16_f32 v10, v14, v15
	v_cvt_pk_bf16_f32 v11, v16, v17
	v_cvt_pk_bf16_f32 v12, v20, v21
	v_cvt_pk_bf16_f32 v13, v22, v23
	v_add_u32_e32 v14, 0x14a42000, v164
	buffer_store_dwordx4 v[10:13], v14, s[56:59], 0 offen sc1
	v_pk_mul_f32 v[6:7], v[6:7], v[18:19] op_sel_hi:[1,0]
	v_pk_mul_f32 v[8:9], v[8:9], v[18:19] op_sel_hi:[1,0]
	v_pk_mul_f32 v[10:11], v[2:3], v[18:19] op_sel_hi:[1,0]
	v_pk_mul_f32 v[12:13], v[4:5], v[18:19] op_sel_hi:[1,0]
	v_cvt_pk_bf16_f32 v2, v6, v7
	v_cvt_pk_bf16_f32 v3, v8, v9
	v_cvt_pk_bf16_f32 v4, v10, v11
	v_cvt_pk_bf16_f32 v5, v12, v13
	buffer_store_dwordx4 v[2:5], v14, s[56:59], 0 offen offset:256 sc1
	s_and_b64 vcc, exec, s[40:41]
	s_mov_b32 s58, s22
	s_mov_b32 s59, s89
	s_cbranch_vccnz .LBB0_112

; #define PG8_WAIT_V(n) asm volatile("s_waitcnt vmcnt(" #n ")" ::: "memory")
; #define PG8_BAR __builtin_amdgcn_s_barrier()
; template <class Epi, class Sched, bool ALIGN_EPI>
; __device__ __forceinline__ void gemm_phase(PG8_LAS unsigned char* lds, const Gemm g, const Sched& S, const Epi& E) {
;     ...
;     PG8_WAIT_V(0);
;     if constexpr (!ALIGN_EPI) { if (wr == 0) PG8_BAR; }
;     PG8_BAR;
.LBB0_112:
	s_waitcnt vmcnt(0)
	s_cmpk_gt_u32 s13, 0xff
	s_cbranch_scc1 .LBB0_114
	v_readlane_b32 vcc_lo, v255, 43
	s_mov_b32 vcc_hi, 0
	s_nop 1
	v_writelane_b32 v255, vcc_hi, 43
	s_cmp_eq_u32 vcc_lo, 1
	s_cbranch_scc1 .LBB0_114
	s_barrier
